# SwiGLU GEMM tile order: grouped 8 m-tiles x 44 n with XCD remap so each XCD streams an 8x8 patch per round (was row-major, n interleaved over XCDs)
# baseline (speedup 1.0000x reference)
; template <int EPI>
; __device__ __forceinline__ void gemm_phase(const bf16_t* A, int lda, const bf16_t* Bt, int ldb, int K, int ntn, void* C, int ldc, char* lds, int bid, int nb, const int tid) {
;   constexpr int GM = 4, nM = MT / 128;
;   const int ntiles = nM * ntn, nig = GM * ntn;
;   const int pos = (EPI != EPI_SWIGLU && (nb & 7) == 0) ? (bid & 7) * (nb >> 3) + (bid >> 3) : bid;
;   for (int L = pos; L < ntiles; L += nb) {
;     int mt, nn;
;     if (EPI == EPI_SWIGLU) { mt = L / ntn; nn = L % ntn; }
;     else { const int gid = L / nig, fm = gid * GM, gsz = min(nM - fm, GM), rem = L - gid * nig; mt = fm + rem % gsz; nn = rem / gsz; }
;     gemm_tile<EPI>(A, lda, Bt, ldb, K, mt * 128, nn * 128, C, ldc, lds, tid);
.LBB0_108:
	v_readlane_b32 s2, v254, 61
	s_cmpk_gt_i32 s2, 0x16db
	s_cbranch_scc1 .LBB0_113
	s_waitcnt vmcnt(2)
	v_lshrrev_b32_e32 v6, 4, v130
	s_mul_i32 s24, s66, 0xb00000
	v_readlane_b32 s2, v253, 29
	v_xor_b32_e32 v0, v6, v130
	v_bfe_u32 v1, v130, 1, 3
	s_mul_hi_i32 s23, s66, 0xb00000
	s_add_u32 s2, s2, s24
	v_readlane_b32 s3, v253, 30
	v_bfe_u32 v7, v130, 4, 2
	v_bitop3_b32 v2, v6, v1, 3 bitop3:0x6c
	v_lshlrev_b32_e32 v0, 4, v0
	v_readlane_b32 s26, v253, 21
	s_addc_u32 s3, s3, s23
	v_and_b32_e32 v131, 15, v130
	v_lshlrev_b32_e32 v175, 4, v2
	v_bitop3_b32 v1, v7, v1, 4 bitop3:0x36
	v_and_b32_e32 v2, 0x70, v0
	v_readlane_b32 s27, v253, 22
	v_bfe_u32 v4, v130, 6, 1
	v_ashrrev_i32_e32 v5, 7, v130
	v_lshlrev_b32_e32 v176, 4, v1
	v_lshl_add_u64 v[0:1], s[26:27], 0, v[2:3]
	v_lshl_add_u64 v[132:133], s[2:3], 0, v[2:3]
	v_lshlrev_b32_e32 v2, 7, v131
	v_readlane_b32 s2, v253, 23
	v_lshl_or_b32 v181, v4, 13, v2
	v_lshl_or_b32 v182, v5, 13, v2
	v_lshlrev_b32_e32 v2, 6, v4
	v_readlane_b32 s3, v253, 24
	v_lshlrev_b32_e32 v183, 6, v5
	v_ashrrev_i32_e32 v174, 3, v130
	v_lshl_add_u64 v[4:5], s[2:3], 0, v[2:3]
	v_lshlrev_b32_e32 v2, 4, v7
	v_readlane_b32 s2, v253, 63
	v_lshl_add_u64 v[134:135], v[4:5], 0, v[2:3]
	v_bitop3_b32 v2, v6, 7, v130 bitop3:0x48
	s_add_u32 s2, s2, s24
	v_readlane_b32 s3, v254, 0
	v_lshlrev_b32_e32 v2, 4, v2
	s_addc_u32 s3, s3, s23
	v_lshl_add_u64 v[136:137], s[2:3], 0, v[2:3]
	v_readlane_b32 s2, v254, 1
	v_readlane_b32 s3, v254, 2
	v_lshlrev_b32_e32 v177, 4, v130
	v_add_u32_e32 v178, 32, v174
	v_add_u32_e32 v179, 64, v174
	v_add_u32_e32 v180, 0x60, v174
	v_lshl_add_u64 v[138:139], s[2:3], 0, v[2:3]
	v_readlane_b32 s23, v254, 61
	s_cmpk_lg_i32 s0, 0x200
	s_cbranch_scc1 .Lsw_noremap
	s_and_b32 s2, s23, 7
	s_lshl_b32 s2, s2, 6
	s_lshr_b32 s23, s23, 3
	s_or_b32 s23, s23, s2
.Lsw_noremap:
.LBB0_110:
	s_mul_hi_u32 s2, s23, 0xba2e8c
	s_mul_i32 s3, s2, 0x160
	s_sub_i32 s3, s23, s3
	s_cmpk_lt_i32 s2, 16
	s_cbranch_scc0 .Lsw_last
	s_lshl_b32 s2, s2, 3
	s_and_b32 s24, s3, 7
	s_add_i32 s2, s2, s24
	s_lshr_b32 s24, s3, 3
	s_branch .Lsw_dec
.Lsw_last:
	s_mul_i32 s24, s3, 0x3334
	s_lshr_b32 s24, s24, 16
	s_mul_i32 s2, s24, 5
	s_sub_i32 s2, s3, s2
	s_addk_i32 s2, 0x80
; template <int EPI>
; __device__ __forceinline__ void gemm_tile(const bf16_t* __restrict__ A, const int lda, const bf16_t* __restrict__ Bt, const int ldb,
;                                           const int K, const int m0, const int n0, void* Cout, const int ldc, char* lds, const int tid) {
;   const int wid = tid >> 6, lane = tid & 63, wr = wid >> 1, wc = wid & 1, fr = lane & 15, fq = lane >> 4;
;   f32x4 acc[4][4];
; #pragma unroll
;   for (int m = 0; m < 4; ++m)
; #pragma unroll
;     for (int n = 0; n < 4; ++n) acc[m][n] = (f32x4){0.f, 0.f, 0.f, 0.f};
;   const int nt = K >> 6;
;   const int st_row = tid >> 3, st_c = (tid & 7) ^ ((tid >> 4) & 7);
;   auto stageA = [&](int kt, int buf) {
; #pragma unroll
;     for (int i = 0; i < 4; ++i) {
;       const int off = tid * 16 + i * 4096, r = st_row + i * 32;
;       const bf16_t* ga = A + (size_t)(m0 + r) * lda + kt * 64 + st_c * 8;
;       __builtin_amdgcn_global_load_lds((const unsigned*)ga, (__attribute__((address_space(3))) unsigned*)(lds + buf * 32768 + off), 16, 0, 0);
;     }
;   };
;   auto stageB = [&](int kt, int buf) {
; #pragma unroll
;     for (int i = 0; i < 4; ++i) {
;       const int off = tid * 16 + i * 4096, r = st_row + i * 32;
;       const bf16_t* gb = Bt + (size_t)(n0 + r) * ldb + kt * 64 + st_c * 8;
;       __builtin_amdgcn_global_load_lds((const unsigned*)gb, (__attribute__((address_space(3))) unsigned*)(lds + buf * 32768 + 16384 + off), 16, 0, 0);
;     }
;   };
;   auto stage = [&](int kt, int buf) { stageA(kt, buf); stageB(kt, buf); };
;   const int fsw = (fr >> 1) & 7;
;   const int xk0 = (fq ^ fsw) << 4, xk1 = ((4 + fq) ^ fsw) << 4;
;   stage(0, 0);
;   for (int kt = 0; kt < nt; ++kt) {
;     asm volatile("s_waitcnt vmcnt(0)" ::: "memory");
;     __syncthreads();
;     if (kt + 1 < nt) stageB(kt + 1, (kt + 1) & 1);
;     const char* sa = lds + (kt & 1) * 32768;
;     const char* sb = sa + 16384;
;     bf16x8 af[2][4], bfr[2][4];
; #pragma unroll
;     for (int ks = 0; ks < 2; ++ks) {
; #pragma unroll
;       for (int m = 0; m < 4; ++m) af[ks][m] = *(const bf16x8*)(sa + (wr * 64 + m * 16 + fr) * 128 + (ks ? xk1 : xk0));
; #pragma unroll
;       for (int n = 0; n < 4; ++n) bfr[ks][n] = *(const bf16x8*)(sb + (wc * 64 + n * 16 + fr) * 128 + (ks ? xk1 : xk0));
;     }
;     if (kt + 1 < nt) stageA(kt + 1, (kt + 1) & 1);
.Lsw_dec:
	s_lshl_b32 s25, s2, 7
	v_add_u32_e32 v4, s25, v174
	v_ashrrev_i32_e32 v5, 31, v4
	v_lshlrev_b64 v[4:5], 11, v[4:5]
	v_readfirstlane_b32 s3, v177
	v_lshl_add_u64 v[6:7], v[0:1], 0, v[4:5]
	s_mov_b32 m0, s3
	v_add_u32_e32 v2, 0x1000, v177
	global_load_lds_dwordx4 v[6:7], off
	v_add_u32_e32 v6, s25, v178
	v_ashrrev_i32_e32 v7, 31, v6
	v_lshlrev_b64 v[6:7], 11, v[6:7]
	v_readfirstlane_b32 s3, v2
	s_waitcnt vmcnt(0)
	v_lshl_add_u64 v[8:9], v[0:1], 0, v[6:7]
	s_mov_b32 m0, s3
	v_add_u32_e32 v2, 0x2000, v177
	global_load_lds_dwordx4 v[8:9], off
	v_add_u32_e32 v8, s25, v179
	v_ashrrev_i32_e32 v9, 31, v8
	v_lshlrev_b64 v[8:9], 11, v[8:9]
	v_readfirstlane_b32 s3, v2
	v_lshl_add_u64 v[10:11], v[0:1], 0, v[8:9]
	s_mov_b32 m0, s3
	v_add_u32_e32 v2, 0x3000, v177
	global_load_lds_dwordx4 v[10:11], off
	v_add_u32_e32 v10, s25, v180
	v_ashrrev_i32_e32 v11, 31, v10
	v_lshlrev_b64 v[10:11], 11, v[10:11]
	v_readfirstlane_b32 s3, v2
	s_lshl_b32 s2, s24, 7
	v_lshl_add_u64 v[12:13], v[0:1], 0, v[10:11]
	s_mov_b32 m0, s3
	v_add_u32_e32 v2, 0x4000, v177
	global_load_lds_dwordx4 v[12:13], off
	v_add_u32_e32 v12, s2, v174
	v_ashrrev_i32_e32 v13, 31, v12
	v_lshlrev_b64 v[12:13], 11, v[12:13]
	v_readfirstlane_b32 s3, v2
	v_lshl_add_u64 v[14:15], v[132:133], 0, v[12:13]
	s_mov_b32 m0, s3
	v_add_u32_e32 v2, 0x5000, v177
	global_load_lds_dwordx4 v[14:15], off
	v_add_u32_e32 v14, s2, v178
	v_ashrrev_i32_e32 v15, 31, v14
	v_lshlrev_b64 v[14:15], 11, v[14:15]
	v_readfirstlane_b32 s3, v2
	v_lshl_add_u64 v[16:17], v[132:133], 0, v[14:15]
	s_mov_b32 m0, s3
	v_add_u32_e32 v2, 0x6000, v177
	global_load_lds_dwordx4 v[16:17], off
	v_add_u32_e32 v16, s2, v179
	v_ashrrev_i32_e32 v17, 31, v16
	v_lshlrev_b64 v[16:17], 11, v[16:17]
	v_readfirstlane_b32 s3, v2
	v_lshl_add_u64 v[18:19], v[132:133], 0, v[16:17]
	s_mov_b32 m0, s3
	v_add_u32_e32 v2, 0x7000, v177
	global_load_lds_dwordx4 v[18:19], off
	v_add_u32_e32 v18, s2, v180
	v_ashrrev_i32_e32 v19, 31, v18
	v_lshlrev_b64 v[18:19], 11, v[18:19]
	v_readfirstlane_b32 s2, v2
	v_lshl_add_u64 v[20:21], v[132:133], 0, v[18:19]
	s_mov_b32 m0, s2
	v_lshl_add_u64 v[148:149], v[138:139], 0, v[4:5]
	global_load_lds_dwordx4 v[20:21], off
	v_mov_b32_e32 v4, 0
	v_lshl_add_u64 v[140:141], v[136:137], 0, v[12:13]
	v_lshl_add_u64 v[142:143], v[136:137], 0, v[14:15]
	v_lshl_add_u64 v[144:145], v[136:137], 0, v[16:17]
	v_lshl_add_u64 v[146:147], v[136:137], 0, v[18:19]
	v_lshl_add_u64 v[150:151], v[138:139], 0, v[6:7]
	v_lshl_add_u64 v[152:153], v[138:139], 0, v[8:9]
	v_lshl_add_u64 v[154:155], v[138:139], 0, v[10:11]
	s_mov_b32 s27, 0
	s_mov_b64 s[2:3], 0
	v_mov_b32_e32 v5, v4
	v_mov_b32_e32 v6, v4
	v_mov_b32_e32 v7, v4
	v_mov_b32_e32 v8, v4
	v_mov_b32_e32 v9, v4
	v_mov_b32_e32 v10, v4
	v_mov_b32_e32 v11, v4
	v_mov_b32_e32 v12, v4
	v_mov_b32_e32 v13, v4
	v_mov_b32_e32 v14, v4
	v_mov_b32_e32 v15, v4
	v_mov_b32_e32 v16, v4
	v_mov_b32_e32 v17, v4
	v_mov_b32_e32 v18, v4
	v_mov_b32_e32 v19, v4
	v_mov_b32_e32 v20, v4
	v_mov_b32_e32 v21, v4
	v_mov_b32_e32 v22, v4
	v_mov_b32_e32 v23, v4
	v_mov_b32_e32 v28, v4
	v_mov_b32_e32 v29, v4
	v_mov_b32_e32 v30, v4
	v_mov_b32_e32 v31, v4
	v_mov_b32_e32 v24, v4
	v_mov_b32_e32 v25, v4
	v_mov_b32_e32 v26, v4
	v_mov_b32_e32 v27, v4
	v_mov_b32_e32 v32, v4
	v_mov_b32_e32 v33, v4
	v_mov_b32_e32 v34, v4
	v_mov_b32_e32 v35, v4
	v_mov_b32_e32 v40, v4
	v_mov_b32_e32 v41, v4
	v_mov_b32_e32 v42, v4
	v_mov_b32_e32 v43, v4
	v_mov_b32_e32 v36, v4
	v_mov_b32_e32 v37, v4
	v_mov_b32_e32 v38, v4
	v_mov_b32_e32 v39, v4
	v_mov_b32_e32 v44, v4
	v_mov_b32_e32 v45, v4
	v_mov_b32_e32 v46, v4
	v_mov_b32_e32 v47, v4
	v_mov_b32_e32 v48, v4
	v_mov_b32_e32 v49, v4
	v_mov_b32_e32 v50, v4
	v_mov_b32_e32 v51, v4
	v_mov_b32_e32 v52, v4
	v_mov_b32_e32 v53, v4
	v_mov_b32_e32 v54, v4
	v_mov_b32_e32 v55, v4
	v_mov_b32_e32 v56, v4
	v_mov_b32_e32 v57, v4
	v_mov_b32_e32 v58, v4
	v_mov_b32_e32 v59, v4
	v_mov_b32_e32 v60, v4
	v_mov_b32_e32 v61, v4
	v_mov_b32_e32 v62, v4
	v_mov_b32_e32 v63, v4
	v_mov_b32_e32 v64, v4
	v_mov_b32_e32 v65, v4
	v_mov_b32_e32 v66, v4
	v_mov_b32_e32 v67, v4
	s_waitcnt vmcnt(0)
	s_barrier
	v_readfirstlane_b32 s100, v177
	s_add_i32 m0, s100, 0xc000
	v_lshl_add_u64 v[226:227], v[140:141], 0, s[2:3]
	global_load_lds_dwordx4 v[226:227], off
	s_add_i32 m0, s100, 0xd000
	v_lshl_add_u64 v[226:227], v[142:143], 0, s[2:3]
	global_load_lds_dwordx4 v[226:227], off
	s_add_i32 m0, s100, 0xe000
	v_lshl_add_u64 v[226:227], v[144:145], 0, s[2:3]
	global_load_lds_dwordx4 v[226:227], off
	s_add_i32 m0, s100, 0xf000
	v_lshl_add_u64 v[226:227], v[146:147], 0, s[2:3]
	global_load_lds_dwordx4 v[226:227], off
	s_add_i32 m0, s100, 0x8000
	v_lshl_add_u64 v[226:227], v[148:149], 0, s[2:3]
	global_load_lds_dwordx4 v[226:227], off
	s_add_i32 m0, s100, 0x9000
	v_lshl_add_u64 v[226:227], v[150:151], 0, s[2:3]
	global_load_lds_dwordx4 v[226:227], off
	s_add_i32 m0, s100, 0xa000
	v_lshl_add_u64 v[226:227], v[152:153], 0, s[2:3]
	global_load_lds_dwordx4 v[226:227], off
	s_add_i32 m0, s100, 0xb000
	v_lshl_add_u64 v[226:227], v[154:155], 0, s[2:3]
	global_load_lds_dwordx4 v[226:227], off
	v_add_u32_e32 v218, v175, v182
	v_add_u32_e32 v220, v175, v181
	ds_read_b128 v[104:107], v218
	ds_read_b128 v[100:103], v218 offset:2048
	ds_read_b128 v[96:99], v218 offset:4096
	ds_read_b128 v[84:87], v218 offset:6144
	ds_read_b128 v[184:187], v220 offset:16384
	ds_read_b128 v[188:191], v220 offset:18432
	ds_read_b128 v[192:195], v220 offset:20480
	ds_read_b128 v[196:199], v220 offset:22528
